# skip the redundant final grid barrier after the last layer's MLP2 (kernel ends right after its stores)
# speedup vs baseline: 1.0050x; 1.0050x over previous
; #define GSYNC() do { XcdBarrier b_; b_.bar = (unsigned*)(p.ws + OFF_BAR); b_.x = xb_xcc_id(); b_.st = (volatile LAS unsigned*)(lds + 131072); xcd_barrier(b_); } while (0)
; __device__ __forceinline__ void xcd_barrier(const XcdBarrier& b) {
;     asm volatile("s_waitcnt vmcnt(0)" ::: "memory");
;     __syncthreads();
;     if (threadIdx.x == 0) {
;         unsigned* bar = b.bar;
;         __builtin_amdgcn_s_waitcnt(0);
;         unsigned nloc = b.st[0], nx = b.st[1];
;         if (nloc == 0u) { xcd_barrier_complete(bar, b.x, nloc, nx); b.st[0] = nloc; b.st[1] = nx; }
; __global__ void __launch_bounds__(NTHREADS, 2) mega_fwd(Params p) {
;     ...
;         GSYNC();
.LBB0_1146:
	v_readlane_b32 s4, v255, 44
	s_cmp_eq_u32 s4, 3
	s_cbranch_scc1 .LBB0_1197
	s_getreg_b32 s4, hwreg(HW_REG_XCC_ID, 0, 4)
	s_waitcnt vmcnt(0)
	s_barrier
	s_and_saveexec_b64 s[0:1], s[84:85]
	v_readlane_b32 s74, v255, 42
	v_readlane_b32 s61, v255, 41
	v_readlane_b32 s75, v255, 43
	s_cbranch_execz .LBB0_182
	v_readlane_b32 s5, v255, 15
	s_waitcnt vmcnt(0) expcnt(0) lgkmcnt(0)
	s_and_b32 s10, s4, 15
	v_mov_b32_e32 v0, s5
	ds_read_b32 v2, v0
	v_readlane_b32 s5, v255, 16
	s_waitcnt lgkmcnt(0)
	v_cmp_ne_u32_e32 vcc, 0, v2
	v_mov_b32_e32 v0, s5
	ds_read_b32 v0, v0
	s_cbranch_vccnz .LBB0_1162
	s_mov_b32 s11, 1
	s_branch .LBB0_1150
